# attention loops: back-edge rotation (loop-head SALU and M0 setup hoisted above the loop-back barrier in MLA and diff loops) on top of MLA V-write hoist + K-frag address dedup
# speedup vs baseline: 1.0116x; 1.0026x over previous
; #define SBAR() __builtin_amdgcn_sched_barrier(0)
; template <int DK, int DV, int LDQ, int LDK, int LDV, int LDO, typename TOut, bool PIPE, bool QL, bool VS>
; __device__ __forceinline__ void attn_body16(const bf16_t* Qb, const bf16_t* Kh, const bf16_t* Vh, TOut* Ob, int seq, char* lds) {
;     ...
;     for (int ks = 0; ks < DK / 32; ++ks) { const bf16x8 qv = *reinterpret_cast<const bf16x8*>(Qb + (long)(wid * QBLK + qt * 16 + c) * LDQ + ks * 32 + g * 8);
;       if constexpr (QL) { *reinterpret_cast<bf16x8*>(Q_lds + (qt * 16 + c) * (DK * 2) + (((ks * 32 + g * 8) * 2) ^ ((c & 7) << 4))) = qv; if (qt == 0 && ks == 0) qr[0][0] = qv; } else qr[qt][ks] = qv; }
;     ...
;   const int vb0 = (int)(uintptr_t)V_lds + (4 * g + (c >> 2)) * VRSB + (c & 3) * 8;
;   struct { bf16x8 vs[VP], ks[PIPE ? KP : 1]; } sr_;
;   const int widu = __builtin_amdgcn_readfirstlane(wid);
;     ...
;   bf16x8 pa[2][2]; const int NT = seq / KVBLK;
;   if constexpr (PIPE) {
;     f32x4 sA[4][2], sB[4][2]; float alA[2], alB[2];
;     SLOAD(0); asm volatile("s_waitcnt vmcnt(0)" ::: "memory"); SWRITE(0); __syncthreads();
;     QKT(sA, K_lds); partialSM16(sA, m_reg, alA, C, THR_S);
;     SLOAD(KVBLK);
;     SWAIT(); SWRITE(1); __syncthreads();
;     for (int j = 1; j + 1 < NT; j += 2) {
;       SLOAD((j + 1) * KVBLK); SBAR(); QKT(sB, K_lds + SHM_K); SBAR();
;       finishSM16(sA, alA, lp, pa); SBAR();
;       pv16<NVT, VRSB>(o, vb0, pa); partialSM16(sB, m_reg, alB, C, THR_S);
;       __syncthreads(); SWAIT(); SWRITE(0);
;       RESC(alB); __syncthreads();
;       SLOAD((j + 2) * KVBLK); SBAR(); QKT(sA, K_lds); SBAR();
;       finishSM16(sB, alB, lp, pa); SBAR();
; __global__ void __launch_bounds__(512, 2) mk_fwd(Args args) {
;     ...
;                 if (uidx < NBIG_M) { const int c = uidx & 255, i = uidx >> 8; bh = (c & 7) * 2 + ((c >> 3) >> 4) + 16 * i; qb = (c >> 3) & 15; small = false; }
;                 else { bh = uidx - NBIG_M - 64; qb = 0; small = true; if (bh < 0) continue; }
;                 const int b = bh >> 3, h = bh & 7; const size_t tk0 = (size_t)b * TPB, tq0 = tk0 + (small ? 0 : CTXL + qb * 256);
;                 att::attn_body16<192, 128, 1536, 1536, 1024, 1024, bf16_t, false, false, false>(QM + tq0 * 1536 + h * 192, KM + tk0 * 1536 + h * 192, VM + tk0 * 1024 + h * 128,
;                                                                             YA + tq0 * 1024 + h * 128, small ? CTXL : TPB, (char*)lds);
.LBB0_673:
	s_andn2_b64 vcc, exec, s[6:7]
	s_cbranch_vccnz .LBB0_668
	s_ashr_i32 s27, s26, 3
	s_and_b32 s28, s26, 7
	s_mul_i32 s7, s27, 0x1100
	s_mul_hi_i32 s6, s27, 0x1100
	s_add_u32 s12, s7, s4
	s_addc_u32 s13, s6, s5
	s_mul_i32 s4, s13, 0xc00
	s_mul_hi_u32 s5, s12, 0xc00
	s_add_i32 s5, s5, s4
	s_mul_i32 s4, s12, 0xc00
	s_add_u32 s4, s1, s4
	s_addc_u32 s5, s16, s5
	s_mul_i32 s33, s28, 0x180
	s_add_u32 s6, s4, s33
	s_addc_u32 s7, s5, 0
	s_mul_i32 s37, s27, 0xcc0000
	v_mov_b32_e32 v22, v0
	s_mul_hi_i32 s36, s27, 0xcc0000
	s_add_u32 s4, s17, s37
	s_addc_u32 s5, s20, s36
	v_add_u32_e32 v17, 0x200, v22
	v_ashrrev_i32_e32 v2, 31, v22
	v_ashrrev_i32_e32 v6, 31, v17
	s_add_u32 s4, s4, s33
	v_ashrrev_i32_e32 v155, 6, v22
	v_bfe_u32 v170, v22, 4, 2
	v_lshrrev_b32_e32 v2, 28, v2
	v_lshrrev_b32_e32 v6, 28, v6
	s_addc_u32 s5, s5, 0
	s_mul_i32 s39, s27, 0x880000
	v_and_b32_e32 v171, 15, v22
	v_lshlrev_b32_e32 v154, 5, v155
	v_lshlrev_b32_e32 v10, 4, v170
	v_mov_b32_e32 v11, v179
	v_add_u32_e32 v2, v22, v2
	v_add_u32_e32 v6, v17, v6
	s_mul_hi_i32 s38, s27, 0x880000
	s_add_u32 s27, s21, s39
	v_or_b32_e32 v15, v154, v171
	v_lshl_add_u64 v[12:13], s[6:7], 0, v[10:11]
	v_ashrrev_i32_e32 v11, 4, v2
	v_and_b32_e32 v2, 0xffffff0, v2
	v_ashrrev_i32_e32 v23, 4, v6
	v_and_b32_e32 v6, 0xffffff0, v6
	s_addc_u32 s29, s22, s38
	s_lshl_b32 s26, s28, 7
	s_lshl_b32 s46, s28, 8
	v_sub_u32_e32 v2, v22, v2
	v_sub_u32_e32 v6, v17, v6
	v_mad_i64_i32 v[18:19], s[6:7], v15, s47, v[12:13]
	v_or_b32_e32 v15, 16, v15
	s_add_u32 s28, s27, s46
	v_lshlrev_b32_e32 v177, 4, v2
	v_lshlrev_b32_e32 v186, 4, v6
	v_mad_i64_i32 v[12:13], s[6:7], v15, s47, v[12:13]
	s_addc_u32 s29, s29, 0
	v_lshl_add_u32 v14, v11, 11, v177
	v_lshl_add_u32 v16, v23, 11, v186
	v_readfirstlane_b32 s6, v155
	s_add_i32 s50, 0, 0x15000
	global_load_dwordx4 v[2:5], v14, s[28:29]
	global_load_dwordx4 v[6:9], v16, s[28:29]
	s_lshl_b32 s28, s6, 10
	s_add_i32 s27, 0, 0x9000
	s_cmp_lg_u32 s27, -1
	s_cselect_b32 s6, s27, 0
	s_add_i32 s28, s28, s6
	s_mov_b32 s6, 0x2aaaaaab
	global_load_dwordx4 v[102:105], v[18:19], off
	global_load_dwordx4 v[94:97], v[18:19], off offset:64
	global_load_dwordx4 v[86:89], v[18:19], off offset:128
	global_load_dwordx4 v[78:81], v[18:19], off offset:192
	global_load_dwordx4 v[70:73], v[18:19], off offset:256
	global_load_dwordx4 v[66:69], v[18:19], off offset:320
	global_load_dwordx4 v[110:113], v[12:13], off
	global_load_dwordx4 v[106:109], v[12:13], off offset:64
	global_load_dwordx4 v[98:101], v[12:13], off offset:128
	global_load_dwordx4 v[90:93], v[12:13], off offset:192
	global_load_dwordx4 v[82:85], v[12:13], off offset:256
	global_load_dwordx4 v[74:77], v[12:13], off offset:320
	v_mul_hi_i32 v12, v22, s6
	v_lshrrev_b32_e32 v13, 31, v12
	v_ashrrev_i32_e32 v12, 2, v12
	v_add_u32_e32 v12, v12, v13
	v_mul_lo_u32 v13, v12, 24
	v_sub_u32_e32 v13, v22, v13
	v_bitop3_b32 v13, v12, v13, 7 bitop3:0x6c
	v_mul_lo_u32 v12, v12, s47
	v_lshl_add_u32 v12, v13, 4, v12
	v_mul_hi_i32 v13, v17, s6
	v_lshrrev_b32_e32 v15, 31, v13
	v_ashrrev_i32_e32 v13, 2, v13
	v_add_u32_e32 v13, v13, v15
	v_mul_lo_u32 v15, v13, 24
	v_sub_u32_e32 v15, v17, v15
	v_bitop3_b32 v15, v13, v15, 7 bitop3:0x6c
	v_mul_lo_u32 v13, v13, s47
	v_lshl_add_u32 v18, v15, 4, v13
	v_add_u32_e32 v13, 0x400, v22
	v_mul_hi_i32 v15, v13, s6
	v_lshrrev_b32_e32 v17, 31, v15
	v_ashrrev_i32_e32 v15, 2, v15
	v_add_u32_e32 v15, v15, v17
	v_mul_lo_u32 v17, v15, 24
	s_mov_b32 m0, s28
	v_sub_u32_e32 v13, v13, v17
	global_load_lds_dwordx4 v12, s[4:5]
	s_add_i32 m0, s28, 0x2000
	v_bitop3_b32 v13, v15, v13, 7 bitop3:0x6c
	v_mul_lo_u32 v15, v15, s47
	global_load_lds_dwordx4 v18, s[4:5]
	v_lshl_add_u32 v20, v13, 4, v15
	s_add_i32 m0, s28, 0x4000
	s_cmp_lg_u32 0, -1
	global_load_lds_dwordx4 v20, s[4:5]
	s_movk_i32 s4, 0x120
	v_mul_lo_u32 v187, v11, s4
	v_add3_u32 v11, 0, v187, v177
	v_mul_lo_u32 v188, v23, s4
	s_waitcnt vmcnt(0)
	s_cselect_b32 s6, 0, 0
	s_add_i32 s30, s30, 1
	v_and_b32_e32 v13, 0x3fffffc0, v22
	v_lshl_add_u32 v24, v13, 2, s50
	v_mov_b32_e32 v13, v179
	v_mov_b32_e32 v19, v179
	v_mov_b32_e32 v21, v179
	v_lshlrev_b32_e32 v178, 4, v171
	s_movk_i32 s4, 0x70
	v_bitop3_b32 v190, v10, v178, s4 bitop3:0x78
	s_movk_i32 s4, 0xc0
	v_mov_b32_e32 v15, v179
	v_mov_b32_e32 v17, v179
	v_mov_b32_e32 v58, v179
	v_mov_b32_e32 v59, v179
	v_mov_b32_e32 v60, v179
	v_mov_b32_e32 v61, v179
	v_lshl_add_u32 v173, v171, 2, v24
	v_add_u32_e32 v172, v24, v10
	v_mov_b32_e32 v156, 0
	v_mov_b64_e32 v[50:51], v[58:59]
	v_mov_b64_e32 v[42:43], v[58:59]
	v_mov_b64_e32 v[34:35], v[58:59]
	v_mov_b64_e32 v[26:27], v[58:59]
	v_mov_b64_e32 v[64:65], v[60:61]
	v_mov_b64_e32 v[54:55], v[58:59]
	v_mov_b64_e32 v[46:47], v[58:59]
	s_waitcnt vmcnt(0)
	ds_write_b128 v11, v[2:5]
	v_add3_u32 v2, 0, v188, v186
	ds_write_b128 v2, v[6:9]
	v_bfe_u32 v2, v22, 2, 2
	v_lshl_or_b32 v2, v170, 2, v2
	v_lshlrev_b32_e32 v3, 3, v22
	v_mul_u32_u24_e32 v2, 0x120, v2
	v_and_b32_e32 v3, 24, v3
	v_add3_u32 v174, v3, s6, v2
	s_or_b32 s6, s37, s33
	s_add_u32 s6, s6, 0x325d0000
	s_addc_u32 s7, s36, 0
	v_and_b32_e32 v4, 0x70, v178
	v_lshl_add_u64 v[158:159], s[6:7], 0, v[12:13]
	v_lshl_add_u64 v[160:161], s[6:7], 0, v[18:19]
	v_lshl_add_u64 v[162:163], s[6:7], 0, v[20:21]
	s_or_b32 s6, s39, s46
	v_bitop3_b32 v193, v10, v4, s4 bitop3:0x36
	s_movk_i32 s4, 0x100
	s_add_u32 s6, s6, 0x358c0000
	v_bitop3_b32 v194, v10, v4, s4 bitop3:0x36
	s_movk_i32 s4, 0x140
	s_addc_u32 s7, s38, 0
	v_bitop3_b32 v191, v10, v4, 64 bitop3:0x36
	v_bitop3_b32 v192, v10, v4, s14 bitop3:0x36
	v_bitop3_b32 v195, v10, v4, s4 bitop3:0x36
	v_lshl_add_u64 v[164:165], s[6:7], 0, v[14:15]
	v_lshl_add_u64 v[166:167], s[6:7], 0, v[16:17]
	v_mov_b64_e32 v[18:19], v[58:59]
	v_mov_b64_e32 v[10:11], v[58:59]
	v_mov_b64_e32 v[2:3], v[58:59]
	v_mov_b64_e32 v[38:39], v[58:59]
	v_mov_b64_e32 v[30:31], v[58:59]
	v_mov_b64_e32 v[22:23], v[58:59]
	v_mov_b64_e32 v[14:15], v[58:59]
	v_mov_b64_e32 v[6:7], v[58:59]
	s_mov_b32 s29, 0
	v_mul_u32_u24_e32 v189, 0x180, v171
	v_cmp_eq_u32_e64 s[4:5], 0, v170
	v_mov_b32_e32 v175, 0xf149f2ca
	v_mov_b64_e32 v[52:53], v[60:61]
	v_mov_b64_e32 v[44:45], v[60:61]
	v_mov_b64_e32 v[36:37], v[60:61]
	v_mov_b64_e32 v[28:29], v[60:61]
	v_mov_b64_e32 v[20:21], v[60:61]
	v_mov_b64_e32 v[12:13], v[60:61]
	v_mov_b64_e32 v[4:5], v[60:61]
	v_mov_b64_e32 v[62:63], v[58:59]
	v_mov_b64_e32 v[56:57], v[60:61]
	v_mov_b64_e32 v[48:49], v[60:61]
	v_mov_b64_e32 v[40:41], v[60:61]
	v_mov_b64_e32 v[32:33], v[60:61]
	v_mov_b64_e32 v[24:25], v[60:61]
	v_mov_b64_e32 v[16:17], v[60:61]
	v_mov_b64_e32 v[8:9], v[60:61]
	v_mov_b32_e32 v176, 0xf149f2ca
	v_mov_b32_e32 v157, v156
	s_waitcnt lgkmcnt(0)
	s_barrier
	s_mov_b64 s[52:53], s[8:9]
	s_mov_b64 s[54:55], s[8:9]
	s_and_b32 s36, s29, 1
	s_xor_b32 s33, s36, 1
	s_mul_i32 s6, s33, 0x6000
	s_add_i32 s6, s6, s28
	s_mov_b32 m0, s6
	s_branch .LBB0_677

; #define SBAR() __builtin_amdgcn_sched_barrier(0)
; template <int NVT, int VRSB, int KB, int DH, int VT> __device__ __forceinline__ void pvh_pro(int vb, s16x4 (&f)[DH + 1][2]) { if constexpr (VT < DH && VT < NVT) { pvh_ld<VT, KB, VRSB>(f[VT], vb); pvh_pro<NVT, VRSB, KB, DH, VT + 1>(vb, f); } }
; __device__ __forceinline__ void partialSM16(f32x4 (&s)[4][2], float (&m_reg)[2], float (&alpha)[2], const float C, const float thr_s) {
;     ...
;   for (int qt = 0; qt < 2; ++qt) { const float mnC = -mn[qt] * C;
; #pragma unroll
;     for (int kt = 0; kt < 4; ++kt)
; #pragma unroll
;       for (int r = 0; r < 4; ++r) s[kt][qt][r] = fmaf(s[kt][qt][r], C, mnC); }
; #pragma unroll
;   for (int qt = 0; qt < 2; ++qt)
; #pragma unroll
;     for (int kt = 0; kt < 2; ++kt)
; #pragma unroll
;       for (int r = 0; r < 4; ++r) s[kt][qt][r] = __builtin_amdgcn_exp2f(s[kt][qt][r]);
; template <int DK, int DV, int LDQ, int LDK, int LDV, int LDO, typename TOut, bool PIPE, bool QL, bool VS>
; __device__ __forceinline__ void attn_body16(const bf16_t* Qb, const bf16_t* Kh, const bf16_t* Vh, TOut* Ob, int seq, char* lds) {
;     ...
;       constexpr int DH = 3; s16x4 pvf[DH + 1][2]; const int vbt = vb0 + vsel * (int)SHM_V;
;       pvh_pro<NVT, VRSB, 0, DH, 0>(vbt, pvf); SBAR();
;       cvt_pa(s, pa, 0); SBAR();
;       pvh_step<NVT, VRSB, 0, DH, true, 0>(o, vbt, pa, pvf, s);
;       pvh_pro<NVT, VRSB, 1, DH, 0>(vbt, pvf); SBAR();
; #pragma unroll
;       for (int qt = 0; qt < 2; ++qt) { float ps = 0.f;
; #pragma unroll
;         for (int kt = 0; kt < 4; ++kt) ps += (s[kt][qt][0] + s[kt][qt][1]) + (s[kt][qt][2] + s[kt][qt][3]);
;         lp[qt] = lp[qt] * al[qt] + ps; }
;       cvt_pa(s, pa, 1); SBAR();
.LBB0_676:
	v_mul_f32_e32 v196, 0xbdd53b94, v176
	v_fmamk_f32 v197, v142, 0x3dd53b94, v196
	v_mul_f32_e32 v142, 0xbdd53b94, v175
	v_fmamk_f32 v122, v122, 0x3dd53b94, v142
	v_fmamk_f32 v123, v123, 0x3dd53b94, v142
	s_mulk_i32 s36, 0x4800
	v_fmamk_f32 v213, v151, 0x3dd53b94, v196
	v_fmamk_f32 v124, v124, 0x3dd53b94, v142
	v_fmamk_f32 v125, v125, 0x3dd53b94, v142
	v_fmamk_f32 v222, v149, 0x3dd53b94, v142
	v_exp_f32_e32 v149, v122
	v_exp_f32_e32 v151, v123
	v_add_u32_e32 v223, s36, v174
	ds_read_b64_tr_b16 v[122:123], v223 offset:0
	v_fmamk_f32 v126, v126, 0x3dd53b94, v196
	v_fmamk_f32 v127, v127, 0x3dd53b94, v196
	v_fmamk_f32 v217, v153, 0x3dd53b94, v196
	v_exp_f32_e32 v153, v124
	v_exp_f32_e32 v183, v125
	ds_read_b64_tr_b16 v[124:125], v223 offset:0x1200
	v_fmamk_f32 v128, v128, 0x3dd53b94, v196
	v_fmamk_f32 v129, v129, 0x3dd53b94, v196
	v_fmamk_f32 v212, v150, 0x3dd53b94, v196
	v_fmamk_f32 v221, v148, 0x3dd53b94, v142
	v_exp_f32_e32 v148, v126
	v_exp_f32_e32 v150, v127
	ds_read_b64_tr_b16 v[126:127], v223 offset:32
	v_fmamk_f32 v215, v152, 0x3dd53b94, v196
	v_fmamk_f32 v130, v130, 0x3dd53b94, v142
	v_fmamk_f32 v131, v131, 0x3dd53b94, v142
	v_exp_f32_e32 v152, v128
	v_exp_f32_e32 v182, v129
	ds_read_b64_tr_b16 v[128:129], v223 offset:0x1220
	v_fmamk_f32 v132, v132, 0x3dd53b94, v142
	v_fmamk_f32 v133, v133, 0x3dd53b94, v142
	v_exp_f32_e32 v185, v130
	v_exp_f32_e32 v199, v131
	ds_read_b64_tr_b16 v[130:131], v223 offset:64
	v_exp_f32_e32 v201, v132
	v_exp_f32_e32 v203, v133
	ds_read_b64_tr_b16 v[132:133], v223 offset:0x1240
	v_fmamk_f32 v134, v134, 0x3dd53b94, v196
	v_fmamk_f32 v135, v135, 0x3dd53b94, v196
	v_fmamk_f32 v136, v136, 0x3dd53b94, v196
	v_fmamk_f32 v137, v137, 0x3dd53b94, v196
	s_add_i32 s29, s29, 1
	v_fmamk_f32 v143, v143, 0x3dd53b94, v196
	v_fmamk_f32 v205, v144, 0x3dd53b94, v196
	v_fmamk_f32 v207, v145, 0x3dd53b94, v196
	v_fmamk_f32 v209, v138, 0x3dd53b94, v142
	v_fmamk_f32 v211, v139, 0x3dd53b94, v142
	v_fmamk_f32 v214, v140, 0x3dd53b94, v142
	v_fmamk_f32 v216, v141, 0x3dd53b94, v142
	v_fmamk_f32 v219, v146, 0x3dd53b94, v142
	v_fmamk_f32 v220, v147, 0x3dd53b94, v142
	v_exp_f32_e32 v184, v134
	v_exp_f32_e32 v198, v135
	v_exp_f32_e32 v200, v136
	v_exp_f32_e32 v202, v137
	v_cvt_pk_bf16_f32 v134, v148, v150
	v_cvt_pk_bf16_f32 v135, v152, v182
	v_cvt_pk_bf16_f32 v136, v184, v198
	v_cvt_pk_bf16_f32 v137, v200, v202
	v_cvt_pk_bf16_f32 v138, v149, v151
	v_cvt_pk_bf16_f32 v139, v153, v183
	v_cvt_pk_bf16_f32 v140, v185, v199
	v_cvt_pk_bf16_f32 v141, v201, v203
	ds_read_b64_tr_b16 v[144:145], v223 offset:0x60
	ds_read_b64_tr_b16 v[146:147], v223 offset:0x1260
	s_waitcnt lgkmcnt(6)
	v_mfma_f32_16x16x32_bf16 v[58:61], v[134:137], v[122:125], v[58:61]
	v_exp_f32_e32 v204, v197
	v_exp_f32_e32 v206, v143
	v_mfma_f32_16x16x32_bf16 v[62:65], v[138:141], v[122:125], v[62:65]
	ds_read_b64_tr_b16 v[122:123], v223 offset:0x80
	ds_read_b64_tr_b16 v[124:125], v223 offset:0x1280
	s_waitcnt lgkmcnt(6)
	v_mfma_f32_16x16x32_bf16 v[50:53], v[134:137], v[126:129], v[50:53]
	v_exp_f32_e32 v208, v205
	v_exp_f32_e32 v210, v207
	v_mfma_f32_16x16x32_bf16 v[54:57], v[138:141], v[126:129], v[54:57]
	ds_read_b64_tr_b16 v[126:127], v223 offset:0xa0
	ds_read_b64_tr_b16 v[128:129], v223 offset:0x12a0
	s_waitcnt lgkmcnt(6)
	v_mfma_f32_16x16x32_bf16 v[42:45], v[134:137], v[130:133], v[42:45]
	v_exp_f32_e32 v205, v209
	v_exp_f32_e32 v207, v211
	v_mfma_f32_16x16x32_bf16 v[46:49], v[138:141], v[130:133], v[46:49]
	ds_read_b64_tr_b16 v[130:131], v223 offset:0xc0
	ds_read_b64_tr_b16 v[132:133], v223 offset:0x12c0
	s_waitcnt lgkmcnt(6)
	v_mfma_f32_16x16x32_bf16 v[34:37], v[134:137], v[144:147], v[34:37]
	v_exp_f32_e32 v209, v214
	v_exp_f32_e32 v211, v216
	v_mfma_f32_16x16x32_bf16 v[38:41], v[138:141], v[144:147], v[38:41]
	ds_read_b64_tr_b16 v[144:145], v223 offset:0xe0
	ds_read_b64_tr_b16 v[146:147], v223 offset:0x12e0
	s_waitcnt lgkmcnt(6)
	v_mfma_f32_16x16x32_bf16 v[26:29], v[134:137], v[122:125], v[26:29]
	v_exp_f32_e32 v212, v212
	v_exp_f32_e32 v214, v213
	v_mfma_f32_16x16x32_bf16 v[30:33], v[138:141], v[122:125], v[30:33]
	s_waitcnt lgkmcnt(4)
	v_mfma_f32_16x16x32_bf16 v[18:21], v[134:137], v[126:129], v[18:21]
	v_exp_f32_e32 v216, v215
	v_exp_f32_e32 v218, v217
	v_mfma_f32_16x16x32_bf16 v[22:25], v[138:141], v[126:129], v[22:25]
	s_waitcnt lgkmcnt(2)
	v_mfma_f32_16x16x32_bf16 v[10:13], v[134:137], v[130:133], v[10:13]
	v_exp_f32_e32 v213, v219
	v_exp_f32_e32 v215, v220
	v_mfma_f32_16x16x32_bf16 v[14:17], v[138:141], v[130:133], v[14:17]
	s_waitcnt lgkmcnt(0)
	v_mfma_f32_16x16x32_bf16 v[2:5], v[134:137], v[144:147], v[2:5]
	v_exp_f32_e32 v217, v221
	v_exp_f32_e32 v219, v222
	v_mfma_f32_16x16x32_bf16 v[6:9], v[138:141], v[144:147], v[6:9]
	ds_read_b64_tr_b16 v[122:123], v223 offset:0x2400
	ds_read_b64_tr_b16 v[124:125], v223 offset:0x3600
	ds_read_b64_tr_b16 v[126:127], v223 offset:0x2420
	ds_read_b64_tr_b16 v[128:129], v223 offset:0x3620
	ds_read_b64_tr_b16 v[130:131], v223 offset:0x2440
	ds_read_b64_tr_b16 v[132:133], v223 offset:0x3640
	v_add_f32_e64 v134, v148, v150
	v_add_f32_e64 v135, v149, v151
	v_pk_add_f32 v[136:137], v[152:153], v[182:183]
	v_pk_add_f32 v[138:139], v[184:185], v[198:199]
	v_pk_add_f32 v[140:141], v[200:201], v[202:203]
	v_pk_add_f32 v[134:135], v[134:135], v[136:137]
	v_pk_add_f32 v[136:137], v[138:139], v[140:141]
	v_pk_add_f32 v[134:135], v[134:135], 0 op_sel_hi:[1,0]
	v_pk_add_f32 v[138:139], v[208:209], v[210:211]
	v_pk_add_f32 v[134:135], v[136:137], v[134:135]
	v_pk_add_f32 v[136:137], v[204:205], v[206:207]
	v_cvt_pk_bf16_f32 v140, v213, v215
	v_pk_add_f32 v[136:137], v[136:137], v[138:139]
	v_pk_add_f32 v[138:139], v[216:217], v[218:219]
	v_pk_add_f32 v[134:135], v[136:137], v[134:135]
	v_pk_add_f32 v[136:137], v[212:213], v[214:215]
	v_cvt_pk_bf16_f32 v141, v217, v219
	v_pk_add_f32 v[136:137], v[136:137], v[138:139]
	v_cvt_pk_bf16_f32 v138, v205, v207
	v_pk_add_f32 v[134:135], v[136:137], v[134:135]
	v_cvt_pk_bf16_f32 v136, v212, v214
	v_pk_fma_f32 v[156:157], v[156:157], v[168:169], v[134:135]
	v_cvt_pk_bf16_f32 v134, v204, v206
	v_cvt_pk_bf16_f32 v135, v208, v210
	v_cvt_pk_bf16_f32 v137, v216, v218
	v_cvt_pk_bf16_f32 v139, v209, v211
	s_mulk_i32 s33, 0x4800
	s_waitcnt vmcnt(0)
; #define SBAR() __builtin_amdgcn_sched_barrier(0)
; template <int N> __device__ __forceinline__ void lgkm_wait() { asm volatile("s_waitcnt lgkmcnt(%0)" :: "i"(N) : "memory"); }
; #define VWRITE(bv) do { _Pragma("unroll") for (int _q = 0; _q < VP; ++_q) *(bf16x8*)(V_lds + (bv) * SHM_V + VROW(_q) * VRSB + VC8(_q) * 16) = sr_.vs[_q]; } while (0)
; template <int NVT, int VRSB, int KB, int DH, bool EXPS, int VT> __device__ __forceinline__ void pvh_step(f32x4 (&o)[2][NVT], int vb, const bf16x8 (&pa)[2][2], s16x4 (&f)[DH + 1][2], f32x4 (&s)[4][2]) {
;   if constexpr (VT < NVT) {
;     if constexpr (VT + DH < NVT) pvh_ld<VT + DH, KB, VRSB>(f[(VT + DH) % (DH + 1)], vb);
;     lgkm_wait<2 * ((NVT - 1 - VT) < DH ? (NVT - 1 - VT) : DH)>(); SBAR();
;     s16x4 (&fa)[2] = f[VT % (DH + 1)];
;     const bf16x8 vf = (bf16x8){fa[0][0], fa[0][1], fa[0][2], fa[0][3], fa[1][0], fa[1][1], fa[1][2], fa[1][3]};
;     o[0][VT] = __builtin_amdgcn_mfma_f32_16x16x32_bf16(pa[0][KB], vf, o[0][VT], 0, 0, 0);
;     o[1][VT] = __builtin_amdgcn_mfma_f32_16x16x32_bf16(pa[1][KB], vf, o[1][VT], 0, 0, 0);
;     if constexpr (EXPS) { constexpr int EPS = 16 / NVT;
; #pragma unroll
;       for (int e = 0; e < EPS; ++e) { constexpr int dummy = 0; (void)dummy; const int idx = VT * EPS + e, kt = 2 + (idx >> 3), qt = (idx >> 2) & 1, r = idx & 3; s[kt][qt][r] = __builtin_amdgcn_exp2f(s[kt][qt][r]); } }
;     SBAR();
;     pvh_step<NVT, VRSB, KB, DH, EXPS, VT + 1>(o, vb, pa, f, s);
;   }
; }
; template <int DK, int DV, int LDQ, int LDK, int LDV, int LDO, typename TOut, bool PIPE, bool QL, bool VS>
; __device__ __forceinline__ void attn_body16(const bf16_t* Qb, const bf16_t* Kh, const bf16_t* Vh, TOut* Ob, int seq, char* lds) {
;     ...
;       pvh_step<NVT, VRSB, 1, DH, false, 0>(o, vbt, pa, pvf, s);
;       if constexpr (VS) {
;         asm volatile("s_waitcnt vmcnt(0)" ::: "memory");
;         __syncthreads();
;         if (j + 1 < NT) VWRITE(0);
;       } else if (j + 1 < NT) { asm volatile("s_waitcnt vmcnt(0)" ::: "memory"); VWRITE(bsel ^ 1); }
;       __syncthreads();
	v_add3_u32 v159, s33, v187, v177
	v_add3_u32 v161, s33, v188, v186
	ds_write_b128 v159, v[118:121]
	ds_write_b128 v161, v[114:117]
	ds_read_b64_tr_b16 v[144:145], v223 offset:0x2460
	ds_read_b64_tr_b16 v[146:147], v223 offset:0x3660
	s_waitcnt lgkmcnt(6)
	s_nop 0
	v_mfma_f32_16x16x32_bf16 v[58:61], v[134:137], v[122:125], v[58:61]
	v_mfma_f32_16x16x32_bf16 v[62:65], v[138:141], v[122:125], v[62:65]
	ds_read_b64_tr_b16 v[122:123], v223 offset:0x2480
	ds_read_b64_tr_b16 v[124:125], v223 offset:0x3680
	s_waitcnt lgkmcnt(6)
	v_mfma_f32_16x16x32_bf16 v[50:53], v[134:137], v[126:129], v[50:53]
	v_mfma_f32_16x16x32_bf16 v[54:57], v[138:141], v[126:129], v[54:57]
	ds_read_b64_tr_b16 v[126:127], v223 offset:0x24a0
	ds_read_b64_tr_b16 v[128:129], v223 offset:0x36a0
	s_waitcnt lgkmcnt(6)
	v_mfma_f32_16x16x32_bf16 v[42:45], v[134:137], v[130:133], v[42:45]
	v_mfma_f32_16x16x32_bf16 v[46:49], v[138:141], v[130:133], v[46:49]
	ds_read_b64_tr_b16 v[130:131], v223 offset:0x24c0
	ds_read_b64_tr_b16 v[132:133], v223 offset:0x36c0
	s_waitcnt lgkmcnt(6)
	v_mfma_f32_16x16x32_bf16 v[34:37], v[134:137], v[144:147], v[34:37]
	v_mfma_f32_16x16x32_bf16 v[38:41], v[138:141], v[144:147], v[38:41]
	ds_read_b64_tr_b16 v[144:145], v223 offset:0x24e0
	ds_read_b64_tr_b16 v[146:147], v223 offset:0x36e0
	s_waitcnt lgkmcnt(6)
	v_mfma_f32_16x16x32_bf16 v[26:29], v[134:137], v[122:125], v[26:29]
	v_mfma_f32_16x16x32_bf16 v[30:33], v[138:141], v[122:125], v[30:33]
	s_waitcnt lgkmcnt(4)
	v_mfma_f32_16x16x32_bf16 v[18:21], v[134:137], v[126:129], v[18:21]
	v_mfma_f32_16x16x32_bf16 v[22:25], v[138:141], v[126:129], v[22:25]
	s_waitcnt lgkmcnt(2)
	v_mfma_f32_16x16x32_bf16 v[10:13], v[134:137], v[130:133], v[10:13]
	v_mfma_f32_16x16x32_bf16 v[14:17], v[138:141], v[130:133], v[14:17]
	s_waitcnt lgkmcnt(0)
	v_mfma_f32_16x16x32_bf16 v[2:5], v[134:137], v[144:147], v[2:5]
	v_mfma_f32_16x16x32_bf16 v[6:9], v[138:141], v[144:147], v[6:9]
	s_waitcnt vmcnt(0)
	s_add_u32 s52, s52, s80
	s_addc_u32 s53, s53, s81
	s_add_u32 s54, s54, s96
	s_addc_u32 s55, s55, s97
	s_and_b32 s36, s29, 1
	s_xor_b32 s33, s36, 1
	s_mul_i32 s6, s33, 0x6000
	s_add_i32 s6, s6, s28
	s_mov_b32 m0, s6
	s_cmp_eq_u32 s30, s29
	s_waitcnt lgkmcnt(0)
	s_barrier
	s_cbranch_scc1 .LBB0_683
; #define SBAR() __builtin_amdgcn_sched_barrier(0)
; template <int N> __device__ __forceinline__ void lgkm_wait() { asm volatile("s_waitcnt lgkmcnt(%0)" :: "i"(N) : "memory"); }
; template <int DK, int D, int I> __device__ __forceinline__ void qk_step(f32x4 (&s)[4][2], bf16x8 (&fr)[D + 1], const int (&ka)[DK / 32], const bf16x8 (&qr)[2][DK / 32]) {
;   constexpr int KS = DK / 32, N = 4 * KS;
;   if constexpr (I < N) {
;     if constexpr (I + D < N) qk_ld<DK, D, I + D>(fr, ka);
;     lgkm_wait<((N - 1 - I) < D ? (N - 1 - I) : D)>(); SBAR();
;     constexpr int kt = I / KS, ks = I % KS;
;     if constexpr (ks == 0) { s[kt][0] = __builtin_amdgcn_mfma_f32_16x16x32_bf16(fr[I % (D + 1)], qr[0][ks], (f32x4){0.f, 0.f, 0.f, 0.f}, 0, 0, 0); s[kt][1] = __builtin_amdgcn_mfma_f32_16x16x32_bf16(fr[I % (D + 1)], qr[1][ks], (f32x4){0.f, 0.f, 0.f, 0.f}, 0, 0, 0); }
;     else { s[kt][0] = __builtin_amdgcn_mfma_f32_16x16x32_bf16(fr[I % (D + 1)], qr[0][ks], s[kt][0], 0, 0, 0); s[kt][1] = __builtin_amdgcn_mfma_f32_16x16x32_bf16(fr[I % (D + 1)], qr[1][ks], s[kt][1], 0, 0, 0); }
;     SBAR();
;     qk_step<DK, D, I + 1>(s, fr, ka, qr);
;   }
; }
; template <int DK, int D, int I> __device__ __forceinline__ void qk_pro(bf16x8 (&fr)[D + 1], const int (&ka)[DK / 32]) { if constexpr (I < D) { qk_ld<DK, D, I>(fr, ka); qk_pro<DK, D, I + 1>(fr, ka); } }
; template <int DK>
; __device__ __forceinline__ void qkt16(f32x4 (&s)[4][2], const char* Ks, const bf16x8 (&qr)[2][DK / 32], int c, int g) {
;   constexpr int D = 4; int ka[DK / 32]; bf16x8 fr[D + 1];
;   const int kb = (int)(uintptr_t)Ks + c * (DK * 2);
; #pragma unroll
;   for (int ks = 0; ks < DK / 32; ++ks) ka[ks] = kb + (((ks * 32 + g * 8) * 2) ^ ((c & 7) << 4));
;   qk_pro<DK, D, 0>(fr, ka); qk_step<DK, D, 0>(s, fr, ka, qr);
; }
; __device__ __forceinline__ void partialSM16(f32x4 (&s)[4][2], float (&m_reg)[2], float (&alpha)[2], const float C, const float thr_s) {
;   float pmax[2];
; #pragma unroll
;   for (int qt = 0; qt < 2; ++qt) { float v = s[0][qt][0];
; #pragma unroll
;     for (int kt = 0; kt < 4; ++kt)
; #pragma unroll
;       for (int r = 0; r < 4; ++r) v = fmaxf(v, s[kt][qt][r]);
;     pmax[qt] = xmax4(v); }
;   float mn[2];
;   if (__builtin_expect(__all(pmax[0] - m_reg[0] <= thr_s && pmax[1] - m_reg[1] <= thr_s), 1)) { mn[0] = m_reg[0]; mn[1] = m_reg[1]; alpha[0] = 1.f; alpha[1] = 1.f; }
.LBB0_677:
	global_load_dwordx4 v[118:121], v164, s[54:55]
	s_nop 0
	global_load_dwordx4 v[114:117], v166, s[54:55]
	s_nop 0
	global_load_lds_dwordx4 v158, s[52:53]
	s_add_i32 m0, s6, 0x2000
	s_nop 0
	global_load_lds_dwordx4 v160, s[52:53]
	s_add_i32 m0, s6, 0x4000
	s_nop 0
	global_load_lds_dwordx4 v162, s[52:53]
	s_cmp_lg_u32 s27, -1
	s_mul_i32 s6, s36, 0x6000
	s_cselect_b32 s7, s27, 0
	s_add_i32 s7, s7, s6
	v_add_u32_e32 v122, s7, v189
	v_add_u32_e32 v168, v122, v190
	v_add_u32_e32 v169, v122, v191
	ds_read_b128 v[122:125], v168 offset:0
	ds_read_b128 v[126:129], v169 offset:0
	ds_read_b128 v[130:133], v168 offset:0x80
	ds_read_b128 v[134:137], v169 offset:0x80
	ds_read_b128 v[138:141], v168 offset:0x100
	s_waitcnt lgkmcnt(4)
	s_nop 0
	v_mfma_f32_16x16x32_bf16 v[142:145], v[122:125], v[102:105], 0
	v_mfma_f32_16x16x32_bf16 v[122:125], v[122:125], v[110:113], 0
	ds_read_b128 v[146:149], v169 offset:0x100
	s_waitcnt lgkmcnt(4)
	v_mfma_f32_16x16x32_bf16 v[142:145], v[126:129], v[94:97], v[142:145]
	v_mfma_f32_16x16x32_bf16 v[122:125], v[126:129], v[106:109], v[122:125]
	ds_read_b128 v[150:153], v168 offset:0x1800
	s_waitcnt lgkmcnt(4)
	v_mfma_f32_16x16x32_bf16 v[126:129], v[130:133], v[86:89], v[142:145]
	v_mfma_f32_16x16x32_bf16 v[122:125], v[130:133], v[98:101], v[122:125]
	ds_read_b128 v[130:133], v169 offset:0x1800
	s_waitcnt lgkmcnt(4)
	v_mfma_f32_16x16x32_bf16 v[126:129], v[134:137], v[78:81], v[126:129]
	v_mfma_f32_16x16x32_bf16 v[122:125], v[134:137], v[90:93], v[122:125]
	ds_read_b128 v[134:137], v168 offset:0x1880
	s_waitcnt lgkmcnt(4)
	v_mfma_f32_16x16x32_bf16 v[126:129], v[138:141], v[70:73], v[126:129]
	v_mfma_f32_16x16x32_bf16 v[122:125], v[138:141], v[82:85], v[122:125]
	ds_read_b128 v[138:141], v169 offset:0x1880
	s_waitcnt lgkmcnt(4)
	v_mfma_f32_16x16x32_bf16 v[126:129], v[146:149], v[66:69], v[126:129]
	v_mfma_f32_16x16x32_bf16 v[122:125], v[146:149], v[74:77], v[122:125]
	ds_read_b128 v[142:145], v168 offset:0x1900
	s_waitcnt lgkmcnt(4)
	v_mfma_f32_16x16x32_bf16 v[146:149], v[150:153], v[102:105], 0
	v_mfma_f32_16x16x32_bf16 v[150:153], v[150:153], v[110:113], 0
	ds_read_b128 v[196:199], v169 offset:0x1900
	s_waitcnt lgkmcnt(4)
	v_mfma_f32_16x16x32_bf16 v[146:149], v[130:133], v[94:97], v[146:149]
	v_mfma_f32_16x16x32_bf16 v[130:133], v[130:133], v[106:109], v[150:153]
	ds_read_b128 v[150:153], v168 offset:0x3000
	s_waitcnt lgkmcnt(4)
	v_mfma_f32_16x16x32_bf16 v[146:149], v[134:137], v[86:89], v[146:149]
	v_mfma_f32_16x16x32_bf16 v[130:133], v[134:137], v[98:101], v[130:133]
	ds_read_b128 v[200:203], v169 offset:0x3000
	s_waitcnt lgkmcnt(4)
	v_mfma_f32_16x16x32_bf16 v[134:137], v[138:141], v[78:81], v[146:149]
	v_mfma_f32_16x16x32_bf16 v[130:133], v[138:141], v[90:93], v[130:133]
	ds_read_b128 v[138:141], v168 offset:0x3080
	s_waitcnt lgkmcnt(4)
	v_mfma_f32_16x16x32_bf16 v[134:137], v[142:145], v[70:73], v[134:137]
	v_mfma_f32_16x16x32_bf16 v[130:133], v[142:145], v[82:85], v[130:133]
	ds_read_b128 v[142:145], v169 offset:0x3080
	s_waitcnt lgkmcnt(4)
	v_mfma_f32_16x16x32_bf16 v[134:137], v[196:199], v[66:69], v[134:137]
	v_mfma_f32_16x16x32_bf16 v[130:133], v[196:199], v[74:77], v[130:133]
	ds_read_b128 v[146:149], v168 offset:0x3100
	s_waitcnt lgkmcnt(4)
	v_mfma_f32_16x16x32_bf16 v[196:199], v[150:153], v[102:105], 0
	v_mfma_f32_16x16x32_bf16 v[150:153], v[150:153], v[110:113], 0
	ds_read_b128 v[204:207], v169 offset:0x3100
	s_waitcnt lgkmcnt(4)
	v_mfma_f32_16x16x32_bf16 v[196:199], v[200:203], v[94:97], v[196:199]
	v_mfma_f32_16x16x32_bf16 v[150:153], v[200:203], v[106:109], v[150:153]
	ds_read_b128 v[200:203], v168 offset:0x4800
	s_waitcnt lgkmcnt(4)
	v_mfma_f32_16x16x32_bf16 v[196:199], v[138:141], v[86:89], v[196:199]
	v_mfma_f32_16x16x32_bf16 v[138:141], v[138:141], v[98:101], v[150:153]
	ds_read_b128 v[150:153], v169 offset:0x4800
	s_waitcnt lgkmcnt(4)
	v_mfma_f32_16x16x32_bf16 v[196:199], v[142:145], v[78:81], v[196:199]
	v_mfma_f32_16x16x32_bf16 v[138:141], v[142:145], v[90:93], v[138:141]
	ds_read_b128 v[208:211], v168 offset:0x4880
	s_waitcnt lgkmcnt(4)
	v_mfma_f32_16x16x32_bf16 v[142:145], v[146:149], v[70:73], v[196:199]
	v_mfma_f32_16x16x32_bf16 v[138:141], v[146:149], v[82:85], v[138:141]
	ds_read_b128 v[146:149], v169 offset:0x4880
	s_waitcnt lgkmcnt(4)
	v_mfma_f32_16x16x32_bf16 v[142:145], v[204:207], v[66:69], v[142:145]
	v_mfma_f32_16x16x32_bf16 v[138:141], v[204:207], v[74:77], v[138:141]
	ds_read_b128 v[196:199], v168 offset:0x4900
	s_waitcnt lgkmcnt(4)
	v_mfma_f32_16x16x32_bf16 v[204:207], v[200:203], v[102:105], 0
	v_mfma_f32_16x16x32_bf16 v[200:203], v[200:203], v[110:113], 0
	ds_read_b128 v[212:215], v169 offset:0x4900
	s_waitcnt lgkmcnt(4)
	v_mfma_f32_16x16x32_bf16 v[204:207], v[150:153], v[94:97], v[204:207]
	v_mfma_f32_16x16x32_bf16 v[150:153], v[150:153], v[106:109], v[200:203]
	s_waitcnt lgkmcnt(3)
	v_mfma_f32_16x16x32_bf16 v[150:153], v[208:211], v[98:101], v[150:153]
	v_mfma_f32_16x16x32_bf16 v[200:203], v[208:211], v[86:89], v[204:207]
	s_waitcnt lgkmcnt(2)
	v_mfma_f32_16x16x32_bf16 v[200:203], v[146:149], v[78:81], v[200:203]
	v_mfma_f32_16x16x32_bf16 v[146:149], v[146:149], v[90:93], v[150:153]
	s_waitcnt lgkmcnt(1)
	v_mfma_f32_16x16x32_bf16 v[150:153], v[196:199], v[70:73], v[200:203]
	v_mfma_f32_16x16x32_bf16 v[146:149], v[196:199], v[82:85], v[146:149]
	s_waitcnt lgkmcnt(0)
	v_mfma_f32_16x16x32_bf16 v[150:153], v[212:215], v[66:69], v[150:153]
	v_mfma_f32_16x16x32_bf16 v[146:149], v[212:215], v[74:77], v[146:149]
	s_nop 1
	v_max_f32_e32 v168, v126, v127
	v_max3_f32 v168, v168, v128, v129
	v_max3_f32 v168, v168, v134, v135
	v_max3_f32 v168, v168, v136, v137
	v_max3_f32 v168, v168, v142, v143
	v_max3_f32 v168, v168, v144, v145
	v_max3_f32 v168, v168, v150, v151
	v_max3_f32 v168, v168, v152, v153
	v_mov_b32_e32 v169, v168
	s_nop 1
	v_permlane16_swap_b32_e32 v168, v169
	v_max_f32_e32 v168, v168, v169
	v_mov_b32_e32 v169, v168
	s_nop 1
	v_permlane32_swap_b32_e32 v168, v169
	v_max_f32_e32 v169, v168, v169
	s_nop 1
	v_max_f32_e32 v168, v122, v123
	v_max3_f32 v168, v168, v124, v125
	v_max3_f32 v168, v168, v130, v131
	v_max3_f32 v168, v168, v132, v133
	v_max3_f32 v168, v168, v138, v139
	v_max3_f32 v168, v168, v140, v141
	v_max3_f32 v168, v168, v146, v147
	v_max3_f32 v168, v168, v148, v149
	v_mov_b32_e32 v182, v168
	s_nop 1
	v_permlane16_swap_b32_e32 v168, v182
	v_max_f32_e32 v168, v168, v182
	v_mov_b32_e32 v182, v168
	s_nop 1
	v_permlane32_swap_b32_e32 v168, v182
	v_max_f32_e32 v196, v168, v182
	v_sub_f32_e32 v168, v169, v176
	v_cmp_ge_f32_e32 vcc, s49, v168
	v_sub_f32_e32 v168, v196, v175
	v_cmp_ge_f32_e64 s[6:7], s49, v168
	s_and_b64 s[6:7], vcc, s[6:7]
	s_cmp_eq_u64 s[6:7], exec
	v_mov_b32_e32 v168, 1.0
	s_cbranch_scc0 .LBB0_682
	v_mov_b32_e32 v169, 1.0

; template <int DK, int DV, int LDQ, int LDK, int LDV, int LDO, typename TOut, bool PIPE, bool QL, bool VS>
; __device__ __forceinline__ void attn_body16(const bf16_t* Qb, const bf16_t* Kh, const bf16_t* Vh, TOut* Ob, int seq, char* lds) {
;     ...
; #pragma unroll
;   for (int qt = 0; qt < 2; ++qt)
; #pragma unroll
;     for (int ks = 0; ks < DK / 32; ++ks) { const bf16x8 qv = *reinterpret_cast<const bf16x8*>(Qb + (long)(wid * QBLK + qt * 16 + c) * LDQ + ks * 32 + g * 8);
;       if constexpr (QL) { *reinterpret_cast<bf16x8*>(Q_lds + (qt * 16 + c) * (DK * 2) + (((ks * 32 + g * 8) * 2) ^ ((c & 7) << 4))) = qv; if (qt == 0 && ks == 0) qr[0][0] = qv; } else qr[qt][ks] = qv; }
;     ...
;   const int vb0 = (int)(uintptr_t)V_lds + (4 * g + (c >> 2)) * VRSB + (c & 3) * 8;
;   struct { bf16x8 vs[VP], ks[PIPE ? KP : 1]; } sr_;
;   const int widu = __builtin_amdgcn_readfirstlane(wid);
.LBB0_698:
	s_ashr_i32 s11, s10, 3
	s_and_b32 s26, s10, 1
	s_mul_i32 s7, s11, 0x1100
	s_mul_hi_i32 s6, s11, 0x1100
	s_add_u32 s8, s7, s4
	s_addc_u32 s9, s6, s5
	s_mul_i32 s4, s9, 0x3080
	s_mul_hi_u32 s5, s8, 0x3080
	s_add_i32 s5, s5, s4
	s_mul_i32 s4, s8, 0x3080
	s_add_u32 s4, s1, s4
	s_addc_u32 s5, s16, s5
	s_lshl_b32 s6, s10, 7
	s_and_b32 s27, s6, 0x300
	s_lshl_b32 s12, s27, 1
	s_add_u32 s4, s4, s12
	s_addc_u32 s5, s5, 0
	s_lshl_b32 s6, s26, 8
	v_mov_b32_e32 v37, v0
	s_add_u32 s4, s4, s6
	s_addc_u32 s5, s5, 0
	v_bfe_u32 v252, v37, 4, 2
	v_ashrrev_i32_e32 v187, 6, v37
	v_lshlrev_b32_e32 v34, 4, v252
	v_mov_b32_e32 v35, v179
	v_and_b32_e32 v253, 15, v37
	v_lshlrev_b32_e32 v186, 5, v187
	v_lshl_add_u64 v[2:3], s[4:5], 0, v[34:35]
	s_mov_b64 s[4:5], 0x1800
	v_or_b32_e32 v20, v186, v253
	v_lshl_add_u64 v[18:19], v[2:3], 0, s[4:5]
	v_mad_i64_i32 v[14:15], s[4:5], v20, s84, v[18:19]
	global_load_dwordx4 v[2:5], v[14:15], off
	global_load_dwordx4 v[6:9], v[14:15], off offset:64
	v_or_b32_e32 v20, 16, v20
	v_mad_i64_i32 v[30:31], s[4:5], v20, s84, v[18:19]
	global_load_dwordx4 v[10:13], v[14:15], off offset:128
	s_nop 0
	global_load_dwordx4 v[14:17], v[14:15], off offset:192
	s_nop 0
	global_load_dwordx4 v[18:21], v[30:31], off
	global_load_dwordx4 v[22:25], v[30:31], off offset:64
	global_load_dwordx4 v[26:29], v[30:31], off offset:128
	s_nop 0
	global_load_dwordx4 v[30:33], v[30:31], off offset:192
	s_mul_hi_i32 s7, s11, 0x3388000
	s_mul_i32 s11, s11, 0x3388000
	s_add_u32 s4, s1, s11
	s_addc_u32 s5, s16, s7
	s_add_u32 s12, s4, s12
	s_addc_u32 s13, s5, 0
	s_add_u32 s4, s12, s6
	s_addc_u32 s5, s13, 0
	s_add_u32 s4, s4, 0x2000
	s_addc_u32 s5, s5, 0
	s_add_u32 s12, s12, 0x2800
	s_addc_u32 s13, s13, 0
	v_and_b32_e32 v36, 0x3fffffc0, v37
	s_add_i32 s33, 0, 0x20800
	v_ashrrev_i32_e32 v49, 31, v37
	v_lshl_add_u32 v45, v36, 2, s33
	v_lshrrev_b32_e32 v36, 27, v49
	v_add_u32_e32 v36, v37, v36
	v_ashrrev_i32_e32 v52, 5, v36
	v_and_b32_e32 v36, 0xfffffe0, v36
	v_sub_u32_e32 v36, v37, v36
	v_lshlrev_b32_e32 v36, 4, v36
	v_add_u32_e32 v53, 0x200, v37
	v_mad_u64_u32 v[38:39], s[36:37], v52, s84, v[36:37]
	v_ashrrev_i32_e32 v54, 31, v53
	v_lshrrev_b32_e32 v39, 27, v54
	v_add_u32_e32 v39, v53, v39
	v_ashrrev_i32_e32 v55, 5, v39
	v_and_b32_e32 v39, 0xfffffe0, v39
	v_sub_u32_e32 v39, v53, v39
	v_lshlrev_b32_e32 v41, 13, v187
	v_lshlrev_b32_e32 v40, 4, v39
	v_mad_u64_u32 v[42:43], s[36:37], v55, s84, v[40:41]
	v_add_u32_e32 v39, 0x400, v37
	v_ashrrev_i32_e32 v43, 31, v39
	v_lshrrev_b32_e32 v43, 27, v43
	v_add_u32_e32 v43, v39, v43
	v_ashrrev_i32_e32 v56, 5, v43
	v_and_b32_e32 v43, 0xfffffe0, v43
	v_sub_u32_e32 v39, v39, v43
	v_lshlrev_b32_e32 v44, 4, v39
	v_add_u32_e32 v39, 0x600, v37
	v_ashrrev_i32_e32 v43, 31, v39
	v_lshrrev_b32_e32 v43, 27, v43
	v_add_u32_e32 v43, v39, v43
	v_ashrrev_i32_e32 v57, 5, v43
	v_and_b32_e32 v43, 0xfffffe0, v43
	v_lshrrev_b32_e32 v35, 4, v37
	s_add_i32 s30, 0, 0x10800
	v_sub_u32_e32 v39, v39, v43
	v_lshlrev_b32_e32 v214, 8, v253
	v_and_b32_e32 v43, 7, v37
	v_add3_u32 v41, s30, v41, v214
	v_bitop3_b32 v35, v35, v43, 3 bitop3:0x6c
	v_lshlrev_b32_e32 v48, 4, v39
	v_lshlrev_b32_e32 v39, 4, v37
	v_lshl_add_u32 v35, v35, 4, v41
	global_load_dwordx4 v[66:69], v38, s[12:13]
	global_load_dwordx4 v[70:73], v42, s[12:13]
	v_and_b32_e32 v39, 0x70, v39
	v_mad_u64_u32 v[46:47], s[36:37], v56, s84, v[44:45]
	v_mad_u64_u32 v[50:51], s[36:37], v57, s84, v[48:49]
	global_load_dwordx4 v[74:77], v46, s[12:13]
	global_load_dwordx4 v[78:81], v50, s[12:13]
	s_cmp_lg_u32 0, -1
	s_cselect_b32 s12, 0, 0
	v_readfirstlane_b32 s13, v187
	s_lshl_b32 s33, s13, 10
	s_add_i32 s30, 0, 0x8800
	s_cmp_lg_u32 s30, -1
	s_waitcnt vmcnt(11)
	ds_write_b128 v35, v[2:5]
	v_or_b32_e32 v2, 64, v34
	v_or_b32_e32 v3, 0x80, v34
	v_or_b32_e32 v4, 0xc0, v34
	v_xad_u32 v2, v2, v39, v41
	v_xad_u32 v3, v3, v39, v41
	v_xad_u32 v4, v4, v39, v41
	s_waitcnt vmcnt(10)
	ds_write_b128 v2, v[6:9]
	s_waitcnt vmcnt(9)
	ds_write_b128 v3, v[10:13]
	s_waitcnt vmcnt(8)
	ds_write_b128 v4, v[14:17]
	s_waitcnt vmcnt(7)
	ds_write_b128 v35, v[18:21] offset:4096
	s_waitcnt vmcnt(6)
	ds_write_b128 v2, v[22:25] offset:4096
	s_waitcnt vmcnt(5)
	ds_write_b128 v3, v[26:29] offset:4096
	s_waitcnt vmcnt(4)
	ds_write_b128 v4, v[30:33] offset:4096
	v_bfe_u32 v2, v37, 2, 2
	v_lshl_or_b32 v2, v252, 2, v2
	v_lshlrev_b32_e32 v3, 3, v37
	v_and_b32_e32 v3, 24, v3
	v_mul_u32_u24_e32 v2, 0x220, v2
	v_add3_u32 v216, v3, s12, v2
	v_lshrrev_b32_e32 v2, 28, v49
	v_add_u32_e32 v2, v37, v2
	v_lshrrev_b32_e32 v4, 28, v54
	v_ashrrev_i32_e32 v3, 4, v2
	v_and_b32_e32 v2, 0xffffff0, v2
	v_add_u32_e32 v4, v53, v4
	s_cselect_b32 s12, s30, 0
	v_sub_u32_e32 v2, v37, v2
	v_ashrrev_i32_e32 v5, 4, v4
	v_and_b32_e32 v4, 0xffffff0, v4
	s_add_i32 s33, s33, s12
	v_bitop3_b32 v2, v3, v2, 7 bitop3:0x6c
	v_mul_lo_u32 v3, v3, s84
	v_sub_u32_e32 v4, v53, v4
	v_lshl_add_u32 v2, v2, 4, v3
	s_mov_b32 m0, s33
	v_bitop3_b32 v4, v5, v4, 7 bitop3:0x6c
	v_mul_lo_u32 v5, v5, s84
	global_load_lds_dwordx4 v2, s[4:5]
	v_lshl_add_u32 v4, v4, 4, v5
	s_add_i32 m0, s33, 0x2000
	v_mul_lo_u32 v6, v52, s86
	global_load_lds_dwordx4 v4, s[4:5]
	v_add_u32_e32 v6, 0, v6
	v_add_u32_e32 v217, v6, v36
	v_mul_lo_u32 v6, v55, s86
	v_add_u32_e32 v6, 0, v6
	s_lshl_b32 s10, s10, 8
	v_add_u32_e32 v218, v6, v40
	v_mul_lo_u32 v6, v56, s86
	s_and_b32 s10, s10, 0x600
	v_add_u32_e32 v6, 0, v6
	s_or_b32 s12, s11, s10
	v_add_u32_e32 v220, v6, v44
	v_mul_lo_u32 v6, v57, s86
	s_add_u32 s10, s21, s12
	v_add_u32_e32 v6, 0, v6
	v_lshlrev_b32_e32 v178, 4, v253
	s_movk_i32 s4, 0x70
	s_addc_u32 s11, s22, s7
	s_or_b32 s6, s12, s6
	v_add_u32_e32 v221, v6, v48
	v_and_b32_e32 v6, 0x70, v178
	v_bitop3_b32 v222, v34, v178, s4 bitop3:0x78
	s_movk_i32 s4, 0xc0
	s_add_u32 s6, s23, s6
	v_mov_b32_e32 v39, v179
	v_mov_b32_e32 v43, v179
	v_mov_b32_e32 v47, v179
	v_mov_b32_e32 v51, v179
	v_mov_b32_e32 v3, v179
	v_mov_b32_e32 v5, v179
	s_waitcnt vmcnt(0)
; #define SBAR() __builtin_amdgcn_sched_barrier(0)
; #define RESC(a) do { if (__any((a) < 1.f)) { if (hi == 0) al_l[r32] = (a); asm volatile("s_waitcnt lgkmcnt(0)" ::: "memory"); \
;     _Pragma("unroll") for (int d = 0; d < 4; ++d) _Pragma("unroll") for (int r = 0; r < 16; ++r) o[d][r] *= al_l[crow(r, hi)]; } } while (0)
; template <int NVT, int VRSB, int KB, int DH, int VT> __device__ __forceinline__ void pvh_pro(int vb, s16x4 (&f)[DH + 1][2]) { if constexpr (VT < DH && VT < NVT) { pvh_ld<VT, KB, VRSB>(f[VT], vb); pvh_pro<NVT, VRSB, KB, DH, VT + 1>(vb, f); } }
; #define VLOAD(k0) do { const char* _vb = (const char*)Vh + (size_t)(k0) * (LDV * 2); \
;     _Pragma("unroll") for (int _q = 0; _q < VP; ++_q) sr_.vs[_q] = *reinterpret_cast<const bf16x8*>(_vb + (unsigned)(VROW(_q) * LDV + VC8(_q) * 8) * 2u); } while (0)
; template <int DK, int DV, int LDQ, int LDK, int LDV, int LDO, typename TOut, bool PIPE, bool QL, bool VS>
; __device__ __forceinline__ void attn_body16(const bf16_t* Qb, const bf16_t* Kh, const bf16_t* Vh, TOut* Ob, int seq, char* lds) {
;     ...
;     for (int j = 0; j < NT; ++j) {
;       const int bsel = j & 1, vsel = VS ? 0 : bsel;
;       if (j + 1 < NT) { VLOAD((j + 1) * KVBLK); KDMA((j + 1) * KVBLK, bsel ^ 1); }
;       SBAR(); QKT(s, K_lds + bsel * SHM_K);
;       partialSM16(s, m_reg, al, C, THR_S);
;       RESC(al);
;       constexpr int DH = 3; s16x4 pvf[DH + 1][2]; const int vbt = vb0 + vsel * (int)SHM_V;
;       pvh_pro<NVT, VRSB, 0, DH, 0>(vbt, pvf); SBAR();
;       cvt_pa(s, pa, 0); SBAR();
;       pvh_step<NVT, VRSB, 0, DH, true, 0>(o, vbt, pa, pvf, s);
;       pvh_pro<NVT, VRSB, 1, DH, 0>(vbt, pvf); SBAR();
; #pragma unroll
;       for (int qt = 0; qt < 2; ++qt) { float ps = 0.f;
; #pragma unroll
;         for (int kt = 0; kt < 4; ++kt) ps += (s[kt][qt][0] + s[kt][qt][1]) + (s[kt][qt][2] + s[kt][qt][3]);
;         lp[qt] = lp[qt] * al[qt] + ps; }
;       cvt_pa(s, pa, 1); SBAR();
;       pvh_step<NVT, VRSB, 1, DH, false, 0>(o, vbt, pa, pvf, s);
;       if constexpr (VS) {
;         asm volatile("s_waitcnt vmcnt(0)" ::: "memory");
;         __syncthreads();
;         if (j + 1 < NT) VWRITE(0);
;       } else if (j + 1 < NT) { asm volatile("s_waitcnt vmcnt(0)" ::: "memory"); VWRITE(bsel ^ 1); }
;       __syncthreads();
	v_bitop3_b32 v224, v34, v6, 64 bitop3:0x36
	v_bitop3_b32 v226, v34, v6, s14 bitop3:0x36
	v_bitop3_b32 v228, v34, v6, s4 bitop3:0x36
	s_addc_u32 s7, s24, s7
	v_mov_b32_e32 v18, v179
	v_mov_b32_e32 v19, v179
	v_mov_b32_e32 v20, v179
	v_mov_b32_e32 v21, v179
	v_add_u32_e32 v223, v41, v222
	v_add_u32_e32 v225, v41, v224
	v_add_u32_e32 v227, v41, v226
	v_add_u32_e32 v229, v41, v228
	v_lshl_add_u32 v219, v253, 2, v45
	v_add_u32_e32 v215, v45, v34
	s_mov_b64 s[56:57], s[10:11]
	s_mov_b64 s[58:59], s[6:7]
	v_mov_b32_e32 v188, v38
	v_mov_b32_e32 v190, v42
	v_mov_b32_e32 v192, v46
	v_mov_b32_e32 v194, v50
	v_mov_b32_e32 v198, v2
	v_mov_b32_e32 v200, v4
	v_mov_b32_e32 v196, 0
	v_mov_b64_e32 v[84:85], v[20:21]
	v_mov_b64_e32 v[88:89], v[20:21]
	v_mov_b64_e32 v[92:93], v[20:21]
	v_mov_b64_e32 v[96:97], v[20:21]
	v_mov_b64_e32 v[100:101], v[20:21]
	v_mov_b64_e32 v[104:105], v[20:21]
	v_mov_b64_e32 v[108:109], v[20:21]
	v_mov_b64_e32 v[112:113], v[20:21]
	v_mov_b64_e32 v[36:37], v[20:21]
	v_mov_b64_e32 v[40:41], v[20:21]
	v_mov_b64_e32 v[44:45], v[20:21]
	v_mov_b64_e32 v[48:49], v[20:21]
	v_mov_b64_e32 v[52:53], v[20:21]
	v_mov_b64_e32 v[56:57], v[20:21]
	v_mov_b64_e32 v[60:61], v[20:21]
	v_mov_b64_e32 v[64:65], v[20:21]
	v_mov_b64_e32 v[116:117], v[20:21]
	v_mov_b64_e32 v[120:121], v[20:21]
	v_mov_b64_e32 v[124:125], v[20:21]
	v_mov_b64_e32 v[128:129], v[20:21]
	v_mov_b64_e32 v[132:133], v[20:21]
	v_mov_b64_e32 v[136:137], v[20:21]
	v_mov_b64_e32 v[140:141], v[20:21]
	v_mov_b64_e32 v[144:145], v[20:21]
	v_mov_b64_e32 v[32:33], v[20:21]
	v_mov_b64_e32 v[28:29], v[20:21]
	v_mov_b64_e32 v[24:25], v[20:21]
	v_mov_b64_e32 v[14:15], v[18:19]
	v_mov_b64_e32 v[10:11], v[18:19]
	v_mov_b64_e32 v[6:7], v[18:19]
	v_mov_b64_e32 v[2:3], v[18:19]
	s_mov_b32 s29, 1
	v_cmp_eq_u32_e64 s[4:5], 0, v252
	v_mov_b32_e32 v230, 0xf149f2ca
	s_mov_b64 s[10:11], 0
	v_mov_b64_e32 v[82:83], v[18:19]
	v_mov_b64_e32 v[86:87], v[18:19]
	v_mov_b64_e32 v[90:91], v[18:19]
	v_mov_b64_e32 v[94:95], v[18:19]
	v_mov_b64_e32 v[98:99], v[18:19]
	v_mov_b64_e32 v[102:103], v[18:19]
	v_mov_b64_e32 v[106:107], v[18:19]
	v_mov_b64_e32 v[110:111], v[18:19]
	v_mov_b64_e32 v[34:35], v[18:19]
	v_mov_b64_e32 v[38:39], v[18:19]
	v_mov_b64_e32 v[42:43], v[18:19]
	v_mov_b64_e32 v[46:47], v[18:19]
	v_mov_b64_e32 v[50:51], v[18:19]
	v_mov_b64_e32 v[54:55], v[18:19]
	v_mov_b64_e32 v[58:59], v[18:19]
	v_mov_b64_e32 v[62:63], v[18:19]
	v_mov_b64_e32 v[114:115], v[18:19]
	v_mov_b64_e32 v[118:119], v[18:19]
	v_mov_b64_e32 v[122:123], v[18:19]
	v_mov_b64_e32 v[126:127], v[18:19]
	v_mov_b64_e32 v[130:131], v[18:19]
	v_mov_b64_e32 v[134:135], v[18:19]
	v_mov_b64_e32 v[138:139], v[18:19]
	v_mov_b64_e32 v[142:143], v[18:19]
	v_mov_b64_e32 v[30:31], v[18:19]
	v_mov_b64_e32 v[26:27], v[18:19]
	v_mov_b64_e32 v[22:23], v[18:19]
	v_mov_b64_e32 v[16:17], v[20:21]
	v_mov_b64_e32 v[12:13], v[20:21]
	v_mov_b64_e32 v[8:9], v[20:21]
	v_mov_b64_e32 v[4:5], v[20:21]
	v_mov_b32_e32 v231, 0xf149f2ca
	v_mov_b32_e32 v197, v196
	s_waitcnt vmcnt(0)
	ds_write_b128 v217, v[66:69]
	ds_write_b128 v218, v[70:73]
	ds_write_b128 v220, v[74:77]
	ds_write_b128 v221, v[78:81]
	s_add_i32 s6, s29, -1
	s_and_b32 s37, s6, 1
	s_lshl_b32 s36, s37, 14
	s_xor_b32 s6, s36, 0x4000
	s_add_i32 s62, s6, s33
	s_add_u32 s52, s56, s10
	s_addc_u32 s53, s57, s11
	s_add_u32 s54, s58, s10
	s_addc_u32 s55, s59, s11
	s_cmp_lt_u32 s29, s28
	s_cselect_b64 s[12:13], -1, 0
	s_waitcnt lgkmcnt(0)
	s_barrier
	s_branch .LBB0_700
.LBB0_699:
	v_pk_add_f32 v[146:147], v[166:167], v[168:169]
	v_pk_add_f32 v[148:149], v[162:163], v[164:165]
	v_pk_add_f32 v[150:151], v[158:159], v[160:161]
	v_pk_add_f32 v[152:153], v[154:155], v[156:157]
	v_pk_add_f32 v[146:147], v[146:147], v[148:149]
	v_pk_add_f32 v[148:149], v[150:151], v[152:153]
	v_pk_add_f32 v[146:147], v[146:147], 0 op_sel_hi:[1,0]
	v_pk_add_f32 v[150:151], v[174:175], v[176:177]
	v_pk_add_f32 v[146:147], v[148:149], v[146:147]
	v_pk_add_f32 v[148:149], v[170:171], v[172:173]
	s_add_u32 s10, s10, 0xc2000
	v_pk_add_f32 v[148:149], v[148:149], v[150:151]
	v_pk_add_f32 v[150:151], v[208:209], v[210:211]
	v_pk_add_f32 v[146:147], v[148:149], v[146:147]
	v_pk_add_f32 v[148:149], v[204:205], v[206:207]
	s_addc_u32 s11, s11, 0
	v_pk_add_f32 v[148:149], v[148:149], v[150:151]
	s_add_i32 s29, s29, 1
	v_pk_add_f32 v[146:147], v[148:149], v[146:147]
	s_add_i32 s6, s29, -1
	s_and_b32 s37, s6, 1
	s_lshl_b32 s36, s37, 14
	s_xor_b32 s6, s36, 0x4000
	s_add_i32 s62, s6, s33
	s_add_u32 s52, s56, s10
	s_addc_u32 s53, s57, s11
	s_add_u32 s54, s58, s10
	s_addc_u32 s55, s59, s11
	s_cmp_lt_u32 s29, s28
	s_cselect_b64 s[12:13], -1, 0
	s_mul_i32 s6, s28, 0xc2000
	v_pk_fma_f32 v[196:197], v[196:197], v[202:203], v[146:147]
	s_cmp_eq_u32 s6, s10
	s_waitcnt lgkmcnt(0)
	s_barrier
	s_cbranch_scc1 .LBB0_713
.LBB0_700:
	s_andn2_b64 vcc, exec, s[12:13]
	s_cbranch_vccnz .LBB0_704
	s_mov_b32 m0, s62
	global_load_dwordx4 v[66:69], v188, s[52:53]
	s_nop 0
	global_load_dwordx4 v[70:73], v190, s[52:53]
	s_nop 0
	global_load_dwordx4 v[74:77], v192, s[52:53]
	s_nop 0
	global_load_dwordx4 v[78:81], v194, s[52:53]
	s_nop 0
	global_load_lds_dwordx4 v198, s[54:55]
	s_add_i32 m0, s62, 0x2000
	s_nop 0
	global_load_lds_dwordx4 v200, s[54:55]
